# E30: pool unit trailing-mean loop: exact power-of-two divisor fast path (s*2^-(g+1)) when all rows have a full window, replaces per-row IEEE division; on E27
# speedup vs baseline: 1.0109x; 1.0109x over previous
.LBB0_484:
	ds_read_u16 v11, v7
	s_add_i32 s42, s42, -1
	v_add_u32_e32 v7, 0xfffffef0, v7
	s_cmp_lg_u32 s42, 0
	s_waitcnt lgkmcnt(0)
	v_lshlrev_b32_e32 v11, 16, v11
	v_add_f32_e32 v9, v9, v11
	s_cbranch_scc1 .LBB0_484
	v_sub_u32_e32 v7, s51, v6
	v_min_i32_e32 v7, 32, v7
	v_add_u32_e32 v7, v7, v6
	v_add_u32_e32 v8, s97, v8
	s_add_i32 s44, s49, 1
	s_mov_b64 s[42:43], 0
	s_mul_i32 s45, s18, 0xfffffef0
	ds_read_u16 v11, v8
	v_add_u32_e32 v19, s45, v8
	ds_read_u16 v18, v19 offset:272
	s_cmp_gt_i32 s49, 0
	s_cbranch_scc1 .Lpoolfast_setup
	s_cmp_lg_u64 s[4:5], 0
	s_cbranch_scc0 .LBB0_486
.Lpoolfast_setup:
	s_add_i32 s46, s58, 1
	s_lshl_b32 s46, s46, 23
	s_sub_i32 s46, 0x3f800000, s46
.Lpoolfast_loop:
	s_waitcnt lgkmcnt(0)
	v_lshlrev_b32_e32 v21, 16, v11
	v_lshlrev_b32_e32 v20, 16, v18
	v_add_u32_e32 v8, 0x110, v8
	v_add_u32_e32 v19, 0x110, v19
	ds_read_u16 v11, v8
	ds_read_u16 v18, v19 offset:272
	v_add_f32_e32 v9, v9, v21
	v_add_u32_e32 v6, 1, v6
	v_mul_f32_e32 v12, s46, v9
	v_sub_f32_e32 v13, v12, v21
	v_cvt_pk_bf16_f32 v13, v13, s0
	ds_write_b16 v8, v13 offset:34816
	v_cmp_ge_i32_e32 vcc, v6, v7
	s_or_b64 s[42:43], vcc, s[42:43]
	v_sub_f32_e32 v9, v9, v20
	s_andn2_b64 exec, exec, s[42:43]
	s_cbranch_execnz .Lpoolfast_loop
	s_branch .LBB0_487
